# P0 prologue: the f32 weights / KV caches it converts once are read with the nt (streaming) hint
# speedup vs baseline: 1.0964x; 1.0199x over previous
.LBB0_25:
	s_cmpk_gt_u32 s82, 0x4df
	s_cbranch_scc0 .LBB0_57
	s_cmpk_gt_u32 s82, 0x5df
	s_cbranch_scc0 .LBB0_54
	s_cmpk_gt_u32 s82, 0xddf
	s_cbranch_scc0 .LBB0_46
	s_cmpk_gt_u32 s82, 0x15df
	s_cbranch_scc0 .LBB0_43
	s_cmpk_gt_u32 s82, 0x161f
	s_cbranch_scc0 .LBB0_37
	s_cmpk_gt_u32 s82, 0x1e1f
	s_cbranch_scc0 .LBB0_32
	s_add_i32 s19, s82, 0xffffe1e0
	s_lshr_b32 s58, s19, 6
	s_lshl_b32 s19, s19, 5
	s_mov_b32 s59, s64
	s_and_b32 s19, s19, 0x7c0
	s_lshl_b64 s[60:61], s[58:59], 20
	s_add_u32 s60, s48, s60
	s_addc_u32 s61, s49, s61
	s_lshl_b32 s65, s19, 9
	s_add_u32 s60, s60, s65
	s_addc_u32 s61, s61, 0
	s_lshl_b32 s65, s82, 6
	s_and_b32 s65, s65, 64
	s_lshl_b32 s66, s65, 2
	s_add_u32 s60, s60, s66
	s_addc_u32 s61, s61, 0
	v_mov_b32_e32 v51, v13
	v_lshl_add_u64 v[70:71], s[60:61], 0, v[50:51]
	v_mov_b32_e32 v27, v13
	v_mov_b32_e32 v29, v13
	s_waitcnt lgkmcnt(0)
	v_lshl_add_u64 v[0:1], v[70:71], 0, v[26:27]
	v_lshl_add_u64 v[4:5], v[70:71], 0, v[28:29]
	global_load_dwordx4 v[0:3], v[0:1], off nt
	s_nop 0
	global_load_dwordx4 v[4:7], v[4:5], off nt
	v_mov_b32_e32 v31, v13
	v_lshl_add_u64 v[66:67], v[70:71], 0, v[30:31]
	global_load_dwordx4 v[66:69], v[66:67], off nt
	v_mov_b32_e32 v33, v13
	v_lshl_add_u64 v[70:71], v[70:71], 0, v[32:33]
	global_load_dwordx4 v[98:101], v[70:71], off nt
	s_lshl_b64 s[58:59], s[58:59], 7
	s_or_b32 s58, s58, s65
	s_mulk_i32 s59, 0x1080
	s_mul_i32 s60, s58, 0x1080
	s_mul_hi_u32 s58, s58, 0x1080
	s_add_i32 s58, s58, s59
	s_add_u32 s59, s3, s60
	s_addc_u32 s60, s33, s58
	s_lshl_b32 s19, s19, 1
	s_add_u32 s58, s59, s19
	v_mov_b32_e32 v53, v13
	s_addc_u32 s59, s60, 0
	v_mov_b32_e32 v55, v13
	v_lshl_add_u64 v[70:71], s[58:59], 0, v[52:53]
	v_mov_b32_e32 v57, v13
	v_lshl_add_u64 v[102:103], v[70:71], 0, v[54:55]
	v_lshl_add_u64 v[70:71], v[70:71], 0, v[56:57]
	s_mov_b64 s[58:59], 0
	s_waitcnt vmcnt(3)
	ds_write2_b32 v77, v0, v1 offset1:1
	ds_write2_b32 v77, v2, v3 offset0:2 offset1:3
	s_waitcnt vmcnt(2)
	ds_write2_b32 v78, v4, v5 offset1:1
	ds_write2_b32 v79, v6, v7 offset1:1
	s_waitcnt vmcnt(1)
	ds_write2_b32 v80, v66, v67 offset1:1
	ds_write2_b32 v81, v68, v69 offset1:1
	s_waitcnt vmcnt(0)
	ds_write2_b32 v82, v98, v99 offset1:1
	ds_write2_b32 v83, v100, v101 offset1:1
	s_waitcnt lgkmcnt(0)
	s_barrier
	ds_read2_b32 v[0:1], v15 offset1:65
	ds_read2_b32 v[2:3], v15 offset0:130 offset1:195
	ds_read2_b32 v[4:5], v86 offset0:4 offset1:69
	ds_read2_b32 v[6:7], v86 offset0:134 offset1:199
	ds_read2_b32 v[66:67], v72 offset1:65
	ds_read2_b32 v[68:69], v72 offset0:130 offset1:195
	ds_read2_b32 v[98:99], v87 offset0:4 offset1:69
	ds_read2_b32 v[100:101], v87 offset0:134 offset1:199
	s_waitcnt lgkmcnt(7)
	v_cvt_pk_bf16_f32 v0, v0, v1
	s_waitcnt lgkmcnt(6)
	v_cvt_pk_bf16_f32 v1, v2, v3
	s_waitcnt lgkmcnt(5)
	v_cvt_pk_bf16_f32 v2, v4, v5
	s_waitcnt lgkmcnt(4)
	v_cvt_pk_bf16_f32 v3, v6, v7
	s_waitcnt lgkmcnt(3)
	v_cvt_pk_bf16_f32 v4, v66, v67
	s_waitcnt lgkmcnt(2)
	v_cvt_pk_bf16_f32 v5, v68, v69
	s_waitcnt lgkmcnt(1)
	v_cvt_pk_bf16_f32 v6, v98, v99
	s_waitcnt lgkmcnt(0)
	v_cvt_pk_bf16_f32 v7, v100, v101
	global_store_dwordx4 v[102:103], v[0:3], off
	global_store_dwordx4 v[70:71], v[4:7], off
	s_barrier
.LBB0_32:
	s_andn2_b64 vcc, exec, s[58:59]
	s_cbranch_vccnz .LBB0_36
	s_add_i32 s19, s82, 0xffffe9e0
	s_lshr_b32 s58, s19, 6
	s_lshl_b32 s19, s19, 5
	s_mov_b32 s59, s64
	s_and_b32 s19, s19, 0x7e0
	s_lshl_b64 s[60:61], s[58:59], 20
	s_add_u32 s59, s46, s60
	s_addc_u32 s61, s47, s61
	s_lshl_b32 s60, s19, 9
	s_add_u32 s60, s59, s60
	s_addc_u32 s61, s61, 0
	s_waitcnt lgkmcnt(0)
	global_load_dwordx4 v[0:3], v58, s[60:61]
	global_load_dwordx4 v[4:7], v58, s[60:61] offset:16
	s_mul_i32 s65, s58, 0x840
	s_mul_hi_u32 s59, s58, 0x840
	s_add_u32 s66, s65, s19
	v_mov_b32_e32 v59, v13
	s_addc_u32 s67, s59, 0
	v_lshl_add_u64 v[70:71], s[60:61], 0, v[58:59]
	s_lshl_b64 s[60:61], s[66:67], 8
	v_add_co_u32_e32 v98, vcc, s57, v70
	v_lshl_add_u64 v[102:103], v[16:17], 0, s[60:61]
	s_nop 0
	v_addc_co_u32_e32 v99, vcc, 0, v71, vcc
	v_lshl_add_u64 v[70:71], v[70:71], 0, s[44:45]
	v_cmp_lt_i32_e32 vcc, v89, v90
	s_waitcnt vmcnt(1)
	v_cvt_pk_bf16_f32 v66, v0, v1
	v_cvt_pk_bf16_f32 v67, v2, v3
	s_waitcnt vmcnt(0)
	v_cvt_pk_bf16_f32 v68, v4, v5
	v_cvt_pk_bf16_f32 v69, v6, v7
	global_store_dwordx4 v[102:103], v[66:69], off
	global_load_dwordx4 v[66:69], v[98:99], off nt
	v_mul_f32_e32 v1, v1, v1
	global_load_dwordx4 v[98:101], v[70:71], off offset:16 nt
	v_mul_f32_e32 v3, v3, v3
	v_fmac_f32_e32 v1, v0, v0
	v_fmac_f32_e32 v3, v2, v2
	v_mul_f32_e32 v5, v5, v5
	v_add_f32_e32 v0, v1, v3
	v_fmac_f32_e32 v5, v4, v4
	v_mul_f32_e32 v7, v7, v7
	v_add_f32_e32 v0, v0, v5
	v_cndmask_b32_e32 v12, v88, v89, vcc
	v_fmac_f32_e32 v7, v6, v6
	v_lshlrev_b32_e32 v12, 2, v12
	v_add_f32_e32 v0, v7, v0
	ds_bpermute_b32 v1, v12, v0
	v_cmp_lt_i32_e32 vcc, v91, v90
	s_waitcnt lgkmcnt(0)
	v_add_f32_e32 v0, v0, v1
	v_cndmask_b32_e32 v27, v88, v91, vcc
	v_cmp_lt_i32_e32 vcc, v92, v90
	s_waitcnt vmcnt(1)
	v_mul_f32_e32 v2, v67, v67
	v_mul_f32_e32 v3, v69, v69
	s_waitcnt vmcnt(0)
	v_mul_f32_e32 v4, v99, v99
	v_fmac_f32_e32 v2, v66, v66
	v_fmac_f32_e32 v3, v68, v68
	v_mul_f32_e32 v5, v101, v101
	v_fmac_f32_e32 v4, v98, v98
	v_add_f32_e32 v2, v2, v3
	v_fmac_f32_e32 v5, v100, v100
	v_add_f32_e32 v2, v2, v4
	v_add_f32_e32 v2, v5, v2
	ds_bpermute_b32 v3, v12, v2
	v_lshlrev_b32_e32 v5, 2, v27
	ds_bpermute_b32 v1, v5, v0
	v_cndmask_b32_e32 v4, v88, v92, vcc
	v_lshlrev_b32_e32 v4, 2, v4
	s_waitcnt lgkmcnt(1)
	v_add_f32_e32 v2, v2, v3
	ds_bpermute_b32 v3, v5, v2
	s_waitcnt lgkmcnt(1)
	v_add_f32_e32 v0, v0, v1
	ds_bpermute_b32 v1, v4, v0
	v_cmp_lt_i32_e32 vcc, v93, v90
	s_waitcnt lgkmcnt(1)
	v_add_f32_e32 v2, v2, v3
	ds_bpermute_b32 v3, v4, v2
	v_cndmask_b32_e32 v5, v88, v93, vcc
	s_waitcnt lgkmcnt(1)
	v_add_f32_e32 v0, v0, v1
	v_lshlrev_b32_e32 v5, 2, v5
	v_cmp_lt_i32_e32 vcc, v94, v90
	s_waitcnt lgkmcnt(0)
	v_add_f32_e32 v1, v2, v3
	v_max3_f32 v0, v0, 0, v1
	ds_bpermute_b32 v1, v5, v0
	v_cndmask_b32_e32 v4, v88, v94, vcc
	v_lshlrev_b32_e32 v6, 2, v4
	v_cvt_pk_bf16_f32 v2, v66, v67
	v_cvt_pk_bf16_f32 v3, v68, v69
	s_waitcnt lgkmcnt(0)
	v_max_f32_e32 v1, v1, v1
	v_max_f32_e32 v0, v0, v1
	ds_bpermute_b32 v1, v6, v0
	v_add_co_u32_e32 v6, vcc, s62, v102
	v_cvt_pk_bf16_f32 v4, v98, v99
	v_cvt_pk_bf16_f32 v5, v100, v101
	v_addc_co_u32_e32 v7, vcc, 0, v103, vcc
	global_store_dwordx4 v[6:7], v[2:5], off
	s_and_saveexec_b64 s[60:61], s[4:5]
	s_cbranch_execz .LBB0_35
	s_waitcnt lgkmcnt(0)
	v_max_f32_e32 v1, v1, v1
	v_max_f32_e32 v0, v0, v0
	s_lshl_b32 s19, s58, 1
	v_max_f32_e32 v0, v0, v1
	v_add_lshl_u32 v1, s19, v73, 2
	global_atomic_umax v1, v0, s[0:1]

.LBB0_37:
	s_andn2_b64 vcc, exec, s[58:59]
	s_cbranch_vccnz .LBB0_42
	s_add_i32 s66, s82, 0xffffea20
	s_mov_b32 s67, s64
	s_lshl_b64 s[58:59], s[66:67], 13
	v_lshl_add_u64 v[4:5], v[18:19], 0, s[58:59]
	s_waitcnt lgkmcnt(0)
	global_load_dwordx4 v[0:3], v[4:5], off nt
	v_mad_u64_u32 v[6:7], s[58:59], s66, v95, v[20:21]
	v_add_co_u32_e32 v4, vcc, 0x1000, v4
	s_waitcnt vmcnt(0)
	global_store_dwordx4 v[6:7], v[0:3], off
	v_addc_co_u32_e32 v5, vcc, 0, v5, vcc
	global_load_dwordx4 v[0:3], v[4:5], off nt
	v_add_co_u32_e32 v4, vcc, 0x1000, v6
	s_nop 1
	v_addc_co_u32_e32 v5, vcc, 0, v7, vcc
	s_waitcnt vmcnt(0)
	global_store_dwordx4 v[4:5], v[0:3], off
	s_and_saveexec_b64 s[58:59], s[6:7]
	s_cbranch_execz .LBB0_41
	s_mul_i32 s60, s66, 0x42000
	v_readlane_b32 s68, v250, 0
	s_mul_hi_u32 s19, s66, 0x42000
	v_readlane_b32 s69, v250, 1
	s_add_u32 s60, s68, s60
	s_addc_u32 s61, s69, s19
	s_lshr_b32 s66, s66, 1
	s_mov_b32 s67, s64
	s_lshl_b32 s19, s82, 6
	s_lshl_b64 s[66:67], s[66:67], 7
	s_and_b32 s19, s19, 64
	s_or_b32 s19, s66, s19
	s_mul_i32 s65, s19, 0x1080
	s_mul_hi_u32 s19, s19, 0x1080
	s_mul_i32 s66, s67, 0x1080
	s_add_i32 s19, s19, s66
	s_add_u32 s72, s68, s65
	s_addc_u32 s73, s69, s19
	s_mov_b64 s[74:75], 0
	v_mov_b32_e32 v0, v204

.LBB0_43:
	s_andn2_b64 vcc, exec, s[58:59]
	s_cbranch_vccnz .LBB0_45
	s_add_i32 s19, s82, 0xfffff220
	s_lshr_b32 s58, s19, 5
	s_lshl_b32 s19, s82, 6
	s_mov_b32 s59, s64
	s_and_b32 s19, s19, 0x7c0
	s_lshl_b64 s[60:61], s[58:59], 19
	s_add_u32 s59, s42, s60
	s_addc_u32 s61, s43, s61
	s_lshl_b32 s60, s19, 8
	s_add_u32 s60, s59, s60
	s_addc_u32 s61, s61, 0
	v_mov_b32_e32 v51, v13
	v_lshl_add_u64 v[70:71], s[60:61], 0, v[50:51]
	v_mov_b32_e32 v61, v13
	v_mov_b32_e32 v35, v13
	s_waitcnt lgkmcnt(0)
	v_lshl_add_u64 v[0:1], v[70:71], 0, v[60:61]
	v_lshl_add_u64 v[4:5], v[70:71], 0, v[34:35]
	global_load_dwordx4 v[0:3], v[0:1], off nt
	s_nop 0
	global_load_dwordx4 v[4:7], v[4:5], off nt
	v_mov_b32_e32 v37, v13
	v_lshl_add_u64 v[66:67], v[70:71], 0, v[36:37]
	global_load_dwordx4 v[66:69], v[66:67], off nt
	v_mov_b32_e32 v39, v13
	v_lshl_add_u64 v[70:71], v[70:71], 0, v[38:39]
	global_load_dwordx4 v[98:101], v[70:71], off nt
	s_mul_hi_u32 s59, s58, 0x42000
	s_mul_i32 s58, s58, 0x42000
	s_add_u32 s58, s34, s58
	s_addc_u32 s59, s35, s59
	s_lshl_b32 s19, s19, 1
	s_add_u32 s58, s58, s19
	v_mov_b32_e32 v53, v13
	s_addc_u32 s59, s59, 0
	v_mov_b32_e32 v55, v13
	v_lshl_add_u64 v[70:71], s[58:59], 0, v[52:53]
	v_mov_b32_e32 v57, v13
	v_lshl_add_u64 v[102:103], v[70:71], 0, v[54:55]
	v_lshl_add_u64 v[70:71], v[70:71], 0, v[56:57]
	s_waitcnt vmcnt(3)
	ds_write2_b32 v77, v0, v1 offset1:1
	ds_write2_b32 v77, v2, v3 offset0:2 offset1:3
	s_waitcnt vmcnt(2)
	ds_write2_b32 v78, v4, v5 offset1:1
	ds_write2_b32 v79, v6, v7 offset1:1
	s_waitcnt vmcnt(1)
	ds_write2_b32 v80, v66, v67 offset1:1
	ds_write2_b32 v81, v68, v69 offset1:1
	s_waitcnt vmcnt(0)
	ds_write2_b32 v82, v98, v99 offset1:1
	ds_write2_b32 v83, v100, v101 offset1:1
	s_waitcnt lgkmcnt(0)
	s_barrier
	ds_read2_b32 v[0:1], v15 offset1:65
	ds_read2_b32 v[2:3], v15 offset0:130 offset1:195
	ds_read2_b32 v[4:5], v86 offset0:4 offset1:69
	ds_read2_b32 v[6:7], v86 offset0:134 offset1:199
	ds_read2_b32 v[66:67], v72 offset1:65
	ds_read2_b32 v[68:69], v72 offset0:130 offset1:195
	ds_read2_b32 v[98:99], v87 offset0:4 offset1:69
	ds_read2_b32 v[100:101], v87 offset0:134 offset1:199
	s_waitcnt lgkmcnt(7)
	v_cvt_pk_bf16_f32 v0, v0, v1
	s_waitcnt lgkmcnt(6)
	v_cvt_pk_bf16_f32 v1, v2, v3
	s_waitcnt lgkmcnt(5)
	v_cvt_pk_bf16_f32 v2, v4, v5
	s_waitcnt lgkmcnt(4)
	v_cvt_pk_bf16_f32 v3, v6, v7
	s_waitcnt lgkmcnt(3)
	v_cvt_pk_bf16_f32 v4, v66, v67
	s_waitcnt lgkmcnt(2)
	v_cvt_pk_bf16_f32 v5, v68, v69
	s_waitcnt lgkmcnt(1)
	v_cvt_pk_bf16_f32 v6, v98, v99
	s_waitcnt lgkmcnt(0)
	v_cvt_pk_bf16_f32 v7, v100, v101
	global_store_dwordx4 v[102:103], v[0:3], off
	global_store_dwordx4 v[70:71], v[4:7], off
	s_barrier

.LBB0_46:
	s_andn2_b64 vcc, exec, s[58:59]
	s_cbranch_vccnz .LBB0_53
	s_add_i32 s19, s82, 0xfffffa20
	s_lshr_b32 s58, s19, 5
	s_lshl_b32 s19, s82, 6
	s_mov_b32 s59, s64
	s_and_b32 s19, s19, 0x7c0
	s_lshl_b64 s[60:61], s[58:59], 19
	s_add_u32 s59, s40, s60
	s_addc_u32 s61, s41, s61
	s_lshl_b32 s60, s19, 8
	s_add_u32 s60, s59, s60
	s_addc_u32 s61, s61, 0
	s_waitcnt lgkmcnt(0)
	global_load_dwordx4 v[0:3], v58, s[60:61]
	global_load_dwordx4 v[4:7], v58, s[60:61] offset:16
	s_mul_i32 s65, s58, 0x840
	s_mul_hi_u32 s59, s58, 0x840
	s_add_u32 s66, s65, s19
	v_mov_b32_e32 v59, v13
	s_addc_u32 s67, s59, 0
	v_lshl_add_u64 v[70:71], s[60:61], 0, v[58:59]
	s_lshl_b64 s[60:61], s[66:67], 7
	v_add_co_u32_e32 v98, vcc, s57, v70
	v_lshl_add_u64 v[102:103], v[22:23], 0, s[60:61]
	s_nop 0
	v_addc_co_u32_e32 v99, vcc, 0, v71, vcc
	v_lshl_add_u64 v[70:71], v[70:71], 0, s[44:45]
	v_cmp_lt_i32_e32 vcc, v89, v90
	s_waitcnt vmcnt(1)
	v_cvt_pk_bf16_f32 v66, v0, v1
	v_cvt_pk_bf16_f32 v67, v2, v3
	s_waitcnt vmcnt(0)
	v_cvt_pk_bf16_f32 v68, v4, v5
	v_cvt_pk_bf16_f32 v69, v6, v7
	global_store_dwordx4 v[102:103], v[66:69], off
	global_load_dwordx4 v[66:69], v[98:99], off nt
	v_mul_f32_e32 v1, v1, v1
	global_load_dwordx4 v[98:101], v[70:71], off offset:16 nt
	v_mul_f32_e32 v3, v3, v3
	v_fmac_f32_e32 v1, v0, v0
	v_fmac_f32_e32 v3, v2, v2
	v_mul_f32_e32 v5, v5, v5
	v_add_f32_e32 v0, v1, v3
	v_fmac_f32_e32 v5, v4, v4
	v_mul_f32_e32 v7, v7, v7
	v_add_f32_e32 v0, v0, v5
	v_cndmask_b32_e32 v12, v88, v89, vcc
	v_fmac_f32_e32 v7, v6, v6
	v_lshlrev_b32_e32 v12, 2, v12
	v_add_f32_e32 v0, v7, v0
	ds_bpermute_b32 v1, v12, v0
	v_cmp_lt_i32_e32 vcc, v91, v90
	s_waitcnt lgkmcnt(0)
	v_add_f32_e32 v0, v0, v1
	v_cndmask_b32_e32 v27, v88, v91, vcc
	v_cmp_lt_i32_e32 vcc, v92, v90
	s_waitcnt vmcnt(1)
	v_mul_f32_e32 v2, v67, v67
	v_mul_f32_e32 v3, v69, v69
	s_waitcnt vmcnt(0)
	v_mul_f32_e32 v4, v99, v99
	v_fmac_f32_e32 v2, v66, v66
	v_fmac_f32_e32 v3, v68, v68
	v_mul_f32_e32 v5, v101, v101
	v_fmac_f32_e32 v4, v98, v98
	v_add_f32_e32 v2, v2, v3
	v_fmac_f32_e32 v5, v100, v100
	v_add_f32_e32 v2, v2, v4
	v_add_f32_e32 v2, v5, v2
	ds_bpermute_b32 v3, v12, v2
	v_lshlrev_b32_e32 v5, 2, v27
	ds_bpermute_b32 v1, v5, v0
	v_cndmask_b32_e32 v4, v88, v92, vcc
	v_lshlrev_b32_e32 v4, 2, v4
	s_waitcnt lgkmcnt(1)
	v_add_f32_e32 v2, v2, v3
	ds_bpermute_b32 v3, v5, v2
	s_waitcnt lgkmcnt(1)
	v_add_f32_e32 v0, v0, v1
	ds_bpermute_b32 v1, v4, v0
	v_cmp_lt_i32_e32 vcc, v96, v90
	s_waitcnt lgkmcnt(1)
	v_add_f32_e32 v2, v2, v3
	ds_bpermute_b32 v3, v4, v2
	v_cndmask_b32_e32 v5, v88, v96, vcc
	s_waitcnt lgkmcnt(1)
	v_add_f32_e32 v0, v0, v1
	v_lshlrev_b32_e32 v5, 2, v5
	v_cmp_lt_i32_e32 vcc, v93, v90
	s_waitcnt lgkmcnt(0)
	v_add_f32_e32 v1, v2, v3
	v_max3_f32 v0, v0, 0, v1
	ds_bpermute_b32 v1, v5, v0
	v_cndmask_b32_e32 v4, v88, v93, vcc
	v_lshlrev_b32_e32 v3, 2, v4
	v_cmp_lt_i32_e32 vcc, v94, v90
	v_cvt_pk_bf16_f32 v4, v98, v99
	s_waitcnt lgkmcnt(0)
	v_max_f32_e32 v1, v1, v1
	v_max_f32_e32 v0, v0, v1
	ds_bpermute_b32 v1, v3, v0
	v_cndmask_b32_e32 v2, v88, v94, vcc
	v_lshlrev_b32_e32 v6, 2, v2
	v_cvt_pk_bf16_f32 v2, v66, v67
	v_cvt_pk_bf16_f32 v3, v68, v69
	s_waitcnt lgkmcnt(0)
	v_max_f32_e32 v1, v1, v1
	v_max_f32_e32 v0, v0, v1
	ds_bpermute_b32 v1, v6, v0
	v_add_co_u32_e32 v6, vcc, s62, v102
	v_cvt_pk_bf16_f32 v5, v100, v101
	s_nop 0
	v_addc_co_u32_e32 v7, vcc, 0, v103, vcc
	global_store_dwordx4 v[6:7], v[2:5], off
	s_and_saveexec_b64 s[60:61], s[8:9]
	s_cbranch_execz .LBB0_52
	s_waitcnt lgkmcnt(0)
	v_max_f32_e32 v1, v1, v1
	v_max_f32_e32 v0, v0, v0
	s_mov_b64 s[66:67], exec
	v_max_f32_e32 v0, v0, v1
	s_mov_b32 s19, 0

.LBB0_54:
	s_andn2_b64 vcc, exec, s[58:59]
	s_cbranch_vccnz .LBB0_56
	s_lshl_b32 s19, s82, 6
	s_and_b32 s19, s19, 0x3c0
	v_readlane_b32 s88, v250, 2
	s_lshl_b32 s58, s19, 12
	v_readlane_b32 s92, v250, 6
	v_readlane_b32 s93, v250, 7
	s_add_u32 s65, s92, s58
	s_addc_u32 s66, s93, 0
	s_lshl_b32 s58, s82, 2
	s_and_b32 s58, s58, 0x1fc0
	s_addk_i32 s58, 0xec80
	s_mov_b32 s59, s64
	s_lshl_b64 s[60:61], s[58:59], 2
	s_add_u32 s60, s65, s60
	s_addc_u32 s61, s66, s61
	v_mov_b32_e32 v51, v13
	v_lshl_add_u64 v[70:71], s[60:61], 0, v[50:51]
	v_mov_b32_e32 v41, v13
	v_mov_b32_e32 v43, v13
	s_waitcnt lgkmcnt(0)
	v_lshl_add_u64 v[0:1], v[70:71], 0, v[40:41]
	v_lshl_add_u64 v[4:5], v[70:71], 0, v[42:43]
	global_load_dwordx4 v[0:3], v[0:1], off nt
	s_nop 0
	global_load_dwordx4 v[4:7], v[4:5], off nt
	v_mov_b32_e32 v45, v13
	v_lshl_add_u64 v[66:67], v[70:71], 0, v[44:45]
	global_load_dwordx4 v[66:69], v[66:67], off nt
	v_mov_b32_e32 v47, v13
	v_lshl_add_u64 v[70:71], v[70:71], 0, v[46:47]
	global_load_dwordx4 v[98:101], v[70:71], off nt
	s_lshl_b64 s[58:59], s[58:59], 11
	s_add_u32 s58, s52, s58
	s_addc_u32 s59, s53, s59
	s_lshl_b32 s19, s19, 1
	s_add_u32 s58, s58, s19
	v_mov_b32_e32 v53, v13
	s_addc_u32 s59, s59, 0
	v_mov_b32_e32 v63, v13
	v_lshl_add_u64 v[70:71], s[58:59], 0, v[52:53]
	v_mov_b32_e32 v65, v13
	v_lshl_add_u64 v[102:103], v[70:71], 0, v[62:63]
	v_readlane_b32 s89, v250, 3
	v_readlane_b32 s90, v250, 4
	v_readlane_b32 s91, v250, 5
	v_readlane_b32 s94, v250, 8
	v_readlane_b32 s95, v250, 9
	v_lshl_add_u64 v[70:71], v[70:71], 0, v[64:65]
	s_waitcnt vmcnt(3)
	ds_write2_b32 v77, v0, v1 offset1:1
	ds_write2_b32 v77, v2, v3 offset0:2 offset1:3
	s_waitcnt vmcnt(2)
	ds_write2_b32 v78, v4, v5 offset1:1
	ds_write2_b32 v79, v6, v7 offset1:1
	s_waitcnt vmcnt(1)
	ds_write2_b32 v80, v66, v67 offset1:1
	ds_write2_b32 v81, v68, v69 offset1:1
	s_waitcnt vmcnt(0)
	ds_write2_b32 v82, v98, v99 offset1:1
	ds_write2_b32 v83, v100, v101 offset1:1
	s_waitcnt lgkmcnt(0)
	s_barrier
	ds_read2_b32 v[0:1], v15 offset1:65
	ds_read2_b32 v[2:3], v15 offset0:130 offset1:195
	ds_read2_b32 v[4:5], v86 offset0:4 offset1:69
	ds_read2_b32 v[6:7], v86 offset0:134 offset1:199
	ds_read2_b32 v[66:67], v72 offset1:65
	ds_read2_b32 v[68:69], v72 offset0:130 offset1:195
	ds_read2_b32 v[98:99], v87 offset0:4 offset1:69
	ds_read2_b32 v[100:101], v87 offset0:134 offset1:199
	s_waitcnt lgkmcnt(7)
	v_cvt_pk_bf16_f32 v0, v0, v1
	s_waitcnt lgkmcnt(6)
	v_cvt_pk_bf16_f32 v1, v2, v3
	s_waitcnt lgkmcnt(5)
	v_cvt_pk_bf16_f32 v2, v4, v5
	s_waitcnt lgkmcnt(4)
	v_cvt_pk_bf16_f32 v3, v6, v7
	s_waitcnt lgkmcnt(3)
	v_cvt_pk_bf16_f32 v4, v66, v67
	s_waitcnt lgkmcnt(2)
	v_cvt_pk_bf16_f32 v5, v68, v69
	s_waitcnt lgkmcnt(1)
	v_cvt_pk_bf16_f32 v6, v98, v99
	s_waitcnt lgkmcnt(0)
	v_cvt_pk_bf16_f32 v7, v100, v101
	global_store_dwordx4 v[102:103], v[0:3], off
	global_store_dwordx4 v[70:71], v[4:7], off
	s_barrier

.LBB0_62:
	s_or_saveexec_b64 s[60:61], s[60:61]
	s_lshl_b32 s19, s82, 6
	s_and_b32 s19, s19, 0x3c0
	v_mov_b32_e32 v0, 0
	s_waitcnt lgkmcnt(0)
	v_mov_b32_e32 v1, 0
	v_mov_b32_e32 v2, 0
	v_mov_b32_e32 v3, 0
	v_mov_b32_e32 v4, 0
	v_mov_b32_e32 v5, 0
	v_mov_b32_e32 v6, 0
	v_mov_b32_e32 v7, 0
	s_xor_b64 exec, exec, s[60:61]
	s_cbranch_execz .LBB0_64
	s_mul_i32 s59, s19, 0x4020
	s_add_u32 s59, s22, s59
	s_addc_u32 s65, s23, 0
	s_lshl_b64 s[66:67], s[66:67], 2
	s_add_u32 s66, s59, s66
	s_addc_u32 s67, s65, s67
	v_mov_b32_e32 v51, v13
	v_lshl_add_u64 v[0:1], s[66:67], 0, v[50:51]
	v_mov_b32_e32 v49, v13
	v_lshl_add_u64 v[0:1], v[0:1], 0, v[48:49]
	v_add_co_u32_e32 v2, vcc, s77, v0
	s_nop 1
	v_addc_co_u32_e32 v3, vcc, 0, v1, vcc
	global_load_dwordx4 v[66:69], v[0:1], off nt
	global_load_dwordx4 v[98:101], v[2:3], off offset:512 nt
	v_add_co_u32_e32 v2, vcc, 0x80000, v0
	s_nop 1
	v_addc_co_u32_e32 v3, vcc, 0, v1, vcc
	v_add_co_u32_e32 v0, vcc, 0xc0000, v0
	s_nop 1
	v_addc_co_u32_e32 v1, vcc, 0, v1, vcc
	global_load_dwordx4 v[4:7], v[2:3], off offset:1024 nt
	s_nop 0
	global_load_dwordx4 v[0:3], v[0:1], off offset:1536 nt
	s_waitcnt vmcnt(3)
	ds_write2_b32 v77, v66, v67 offset1:1
	ds_write2_b32 v77, v68, v69 offset0:2 offset1:3
	s_waitcnt vmcnt(2)
	ds_write2_b32 v78, v98, v99 offset1:1
	ds_write2_b32 v79, v100, v101 offset1:1
